# attention: running-max reference subtracted by a 7th k-step MFMA (bf16-exact reference), cross-half max exchange only on the rare rescale path
# speedup vs baseline: 1.0493x; 1.0161x over previous
; #define LAS __attribute__((address_space(3)))
; #define DMAT(kt, so) do { const unsigned rb_ = (unsigned)ROWBASE(kt); _Pragma("unroll") for (int r = 0; r < 3; ++r) if (wid + 8 * r < 22) \
;         __builtin_amdgcn_global_load_lds((const unsigned*)(dsrc[r] + (size_t)rb_ * dmul[r]), (LAS unsigned*)(lds + (so) + dlds[r]), 16, 0, 0); } while (0)
; __device__ __forceinline__ void attn_unit2(LAS unsigned char* lds, const bf16_t* __restrict__ Q, const bf16_t* __restrict__ KN, const bf16_t* __restrict__ KPE, ...
;     ...
;     __syncthreads();
;     int sc = 0, sn = SLOT, snn = 2 * SLOT;
;     f32x16 oa0 = {}, oa1 = {}, ob0 = {}, ob1 = {};
;     float ma = -1.0e30f, mb = -1.0e30f, la = 0.f, lb = 0.f;
;     for (int t = 0; t < ntiles; ++t) {
;         __builtin_amdgcn_sched_barrier(0);
;         f32x16 sa0 = {}, sa1 = {}, sb0 = {}, sb1 = {};
;         const LAS unsigned char* ka = lds + sc + ka_off;
; #pragma unroll
;         for (int ds = 0; ds < 6; ++ds) {
;             const bf16x8 k0 = *(const LAS bf16x8*)(ka + ds * 32);
;             const bf16x8 k1 = *(const LAS bf16x8*)(ka + 32 * KROW + ds * 32);
;             sa0 = __builtin_amdgcn_mfma_f32_32x32x16_bf16(k0, qa[ds], sa0, 0, 0, 0);
;             sa1 = __builtin_amdgcn_mfma_f32_32x32x16_bf16(k1, qa[ds], sa1, 0, 0, 0);
;             sb0 = __builtin_amdgcn_mfma_f32_32x32x16_bf16(k0, qb[ds], sb0, 0, 0, 0);
;             sb1 = __builtin_amdgcn_mfma_f32_32x32x16_bf16(k1, qb[ds], sb1, 0, 0, 0);
;         }
;         __builtin_amdgcn_sched_barrier(0);
;         if (t + 2 < ntiles) DMAT(t + 2, snn);
;         u32x4 pa[4], pb[4];
.LBB0_354:
	v_and_b32_e32 v0, 19, v3
	v_lshlrev_b32_e32 v1, 1, v3
	v_lshrrev_b32_e32 v3, 1, v3
	v_and_b32_e32 v1, 8, v1
	v_and_b32_e32 v3, 4, v3
	v_or3_b32 v0, v0, v1, v3
	v_mov_b32_e32 v16, v129
	v_mov_b32_e32 v17, v129
	v_mov_b32_e32 v30, v129
	v_mov_b32_e32 v31, v129
	v_mul_u32_u24_e32 v183, 0xd0, v0
	v_mul_u32_u24_e32 v187, 0x90, v2
	v_mov_b32_e32 v18, v129
	v_mov_b32_e32 v19, v129
	v_mov_b32_e32 v20, v129
	v_mov_b32_e32 v21, v129
	v_mov_b32_e32 v22, v129
	v_mov_b32_e32 v23, v129
	v_mov_b32_e32 v24, v129
	v_mov_b32_e32 v25, v129
	v_mov_b32_e32 v26, v129
	v_mov_b32_e32 v27, v129
	v_mov_b32_e32 v28, v129
	v_mov_b32_e32 v29, v129
	v_mov_b64_e32 v[62:63], v[30:31]
	v_mov_b64_e32 v[46:47], v[30:31]
	v_mov_b64_e32 v[0:1], v[16:17]
	s_add_i32 s10, s14, 0x4080
	s_add_i32 s11, s24, 0xffffff80
	s_mov_b32 s24, 0
	v_mov_b32_e32 v191, 0
	v_mov_b32_e32 v194, 0xf149f2ca
	s_mov_b32 s25, 0xb000
	s_movk_i32 s26, 0x5800
	s_mov_b32 s14, 0
	v_mov_b64_e32 v[60:61], v[28:29]
	v_mov_b64_e32 v[58:59], v[26:27]
	v_mov_b64_e32 v[56:57], v[24:25]
	v_mov_b64_e32 v[54:55], v[22:23]
	v_mov_b64_e32 v[52:53], v[20:21]
	v_mov_b64_e32 v[50:51], v[18:19]
	v_mov_b64_e32 v[48:49], v[16:17]
	v_mov_b64_e32 v[44:45], v[28:29]
	v_mov_b64_e32 v[42:43], v[26:27]
	v_mov_b64_e32 v[40:41], v[24:25]
	v_mov_b64_e32 v[38:39], v[22:23]
	v_mov_b64_e32 v[36:37], v[20:21]
	v_mov_b64_e32 v[34:35], v[18:19]
	v_mov_b64_e32 v[32:33], v[16:17]
	v_mov_b64_e32 v[2:3], v[18:19]
	v_mov_b64_e32 v[4:5], v[20:21]
	v_mov_b64_e32 v[6:7], v[22:23]
	v_mov_b64_e32 v[8:9], v[24:25]
	v_mov_b64_e32 v[10:11], v[26:27]
	v_mov_b64_e32 v[12:13], v[28:29]
	v_mov_b64_e32 v[14:15], v[30:31]
	v_mov_b32_e32 v195, 0xf149f2ca
	v_mov_b32_e32 v193, 0
	s_mov_b32 s27, 0
	s_waitcnt vmcnt(0) lgkmcnt(0)
	s_barrier
	s_mov_b32 s34, s14
	v_mov_b32_e32 v96, 0
	v_mov_b32_e32 v97, 0
	v_mov_b32_e32 v98, 0
	v_mov_b32_e32 v99, 0
	v_mov_b32_e32 v100, 0
	v_mov_b32_e32 v101, 0
	v_mov_b32_e32 v102, 0
	v_mov_b32_e32 v103, 0
	v_mov_b32_e32 v112, 0
	v_mov_b32_e32 v113, 0
	v_mov_b32_e32 v114, 0
	v_mov_b32_e32 v115, 0
	v_mov_b32_e32 v116, 0
	v_mov_b32_e32 v117, 0
	v_mov_b32_e32 v118, 0
	v_mov_b32_e32 v119, 0
	v_sub_u32_e32 v228, 1, v192
	v_mul_u32_u24_e32 v228, 0xffff, v228
	v_and_b32_e32 v240, 0x3f80, v228
	v_mov_b32_e32 v241, 0
	v_mov_b32_e32 v242, 0
	v_mov_b32_e32 v243, 0
	v_and_b32_e32 v244, 0x4480, v228
	v_mov_b32_e32 v245, 0
	v_mov_b32_e32 v246, 0
	v_mov_b32_e32 v247, 0
	v_mov_b32_e32 v194, 0xc4800000
	v_and_b32_e32 v248, 0x4480, v228
	v_mov_b32_e32 v249, 0
	v_mov_b32_e32 v250, 0
	v_mov_b32_e32 v251, 0
	v_mov_b32_e32 v195, 0xc4800000
	v_add3_u32 v224, s34, v183, v128
	ds_read_b128 v[212:215], v224 offset:0
	ds_read_b128 v[216:219], v224 offset:32
	ds_read_b128 v[220:223], v224 offset:64
	v_mfma_f32_32x32x16_bf16 v[64:79], v[240:243], v[244:247], 0
	v_mfma_f32_32x32x16_bf16 v[80:95], v[240:243], v[248:251], 0
	s_waitcnt lgkmcnt(2)
	v_mfma_f32_32x32x16_bf16 v[64:79], v[212:215], v[130:133], v[64:79]
	v_mfma_f32_32x32x16_bf16 v[80:95], v[212:215], v[138:141], v[80:95]
	ds_read_b128 v[212:215], v224 offset:96
	s_waitcnt lgkmcnt(2)
	v_mfma_f32_32x32x16_bf16 v[64:79], v[216:219], v[134:137], v[64:79]
	v_mfma_f32_32x32x16_bf16 v[80:95], v[216:219], v[142:145], v[80:95]
	ds_read_b128 v[216:219], v224 offset:128
	s_waitcnt lgkmcnt(2)
	v_mfma_f32_32x32x16_bf16 v[64:79], v[220:223], v[146:149], v[64:79]
	v_mfma_f32_32x32x16_bf16 v[80:95], v[220:223], v[154:157], v[80:95]
	ds_read_b128 v[220:223], v224 offset:160
	s_waitcnt lgkmcnt(2)
	v_mfma_f32_32x32x16_bf16 v[64:79], v[212:215], v[150:153], v[64:79]
	v_mfma_f32_32x32x16_bf16 v[80:95], v[212:215], v[158:161], v[80:95]
	s_waitcnt lgkmcnt(1)
	v_mfma_f32_32x32x16_bf16 v[64:79], v[216:219], v[162:165], v[64:79]
	v_mfma_f32_32x32x16_bf16 v[80:95], v[216:219], v[170:173], v[80:95]
	s_waitcnt lgkmcnt(0)
	v_mfma_f32_32x32x16_bf16 v[64:79], v[220:223], v[166:169], v[64:79]
	v_mfma_f32_32x32x16_bf16 v[80:95], v[220:223], v[174:177], v[80:95]
	v_add3_u32 v225, s34, v187, v128
	ds_read_b128 v[196:199], v225 offset:13376
	ds_read_b128 v[200:203], v225 offset:17984
	ds_read_b128 v[204:207], v225 offset:13408
	ds_read_b128 v[208:211], v225 offset:18016
	s_nop 7
	s_nop 3
.Lat_loop:
	v_add3_u32 v224, s34, v183, v128
	ds_read_b128 v[212:215], v224 offset:6656
	ds_read_b128 v[216:219], v224 offset:6688
	ds_read_b128 v[220:223], v224 offset:6720
	s_waitcnt lgkmcnt(6)
	v_mfma_f32_32x32x16_bf16 v[16:31], v[196:199], v[96:99], v[16:31]
	v_max3_f32 v226, v64, v65, v66
	v_max3_f32 v227, v67, v68, v69
	s_waitcnt lgkmcnt(5)
	v_mfma_f32_32x32x16_bf16 v[48:63], v[200:203], v[96:99], v[48:63]
	v_max3_f32 v226, v226, v70, v71
	v_max3_f32 v227, v227, v72, v73
	s_waitcnt lgkmcnt(4)
	v_mfma_f32_32x32x16_bf16 v[16:31], v[204:207], v[100:103], v[16:31]
	v_max3_f32 v226, v226, v74, v75
	v_max3_f32 v227, v227, v76, v77
	s_waitcnt lgkmcnt(3)
	v_mfma_f32_32x32x16_bf16 v[48:63], v[208:211], v[100:103], v[48:63]
	v_max3_f32 v226, v226, v78, v79
	v_max_f32_e32 v226, v226, v227
	v_cmp_lt_f32_e32 vcc, s33, v226
	s_cbranch_vccnz .Lat_resc_aE
; #define LAS __attribute__((address_space(3)))
; #define DMAT(kt, so) do { const unsigned rb_ = (unsigned)ROWBASE(kt); _Pragma("unroll") for (int r = 0; r < 3; ++r) if (wid + 8 * r < 22) \
;         __builtin_amdgcn_global_load_lds((const unsigned*)(dsrc[r] + (size_t)rb_ * dmul[r]), (LAS unsigned*)(lds + (so) + dlds[r]), 16, 0, 0); } while (0)
; __device__ __forceinline__ void attn_unit2(LAS unsigned char* lds, const bf16_t* __restrict__ Q, const bf16_t* __restrict__ KN, const bf16_t* __restrict__ KPE, ...
;     ...
;         f32x16 sa0 = {}, sa1 = {}, sb0 = {}, sb1 = {};
;         const LAS unsigned char* ka = lds + sc + ka_off;
; #pragma unroll
;         for (int ds = 0; ds < 6; ++ds) {
;             const bf16x8 k0 = *(const LAS bf16x8*)(ka + ds * 32);
;             const bf16x8 k1 = *(const LAS bf16x8*)(ka + 32 * KROW + ds * 32);
;             sa0 = __builtin_amdgcn_mfma_f32_32x32x16_bf16(k0, qa[ds], sa0, 0, 0, 0);
;             sa1 = __builtin_amdgcn_mfma_f32_32x32x16_bf16(k1, qa[ds], sa1, 0, 0, 0);
;             sb0 = __builtin_amdgcn_mfma_f32_32x32x16_bf16(k0, qb[ds], sb0, 0, 0, 0);
;             sb1 = __builtin_amdgcn_mfma_f32_32x32x16_bf16(k1, qb[ds], sb1, 0, 0, 0);
;         }
;         __builtin_amdgcn_sched_barrier(0);
;         if (t + 2 < ntiles) DMAT(t + 2, snn);
;         u32x4 pa[4], pb[4];
;     ...
;         SOFTMAX2(sa0, sa1, ma, la, oa0, oa1, pa);
;         SOFTMAX2(sb0, sb1, mb, lb, ob0, ob1, pb);
;     ...
;         const LAS unsigned char* va = lds + sc + va_off;
; #pragma unroll
;         for (int st = 0; st < 4; ++st) {
;             const bf16x8 v0 = *(const LAS bf16x8*)(va + st * 32);
;             const bf16x8 v1 = *(const LAS bf16x8*)(va + 32 * VROW + st * 32);
;             const bf16x8 fa = __builtin_bit_cast(bf16x8, pa[st]), fb = __builtin_bit_cast(bf16x8, pb[st]);
;             oa0 = __builtin_amdgcn_mfma_f32_32x32x16_bf16(v0, fa, oa0, 0, 0, 0);
;             oa1 = __builtin_amdgcn_mfma_f32_32x32x16_bf16(v1, fa, oa1, 0, 0, 0);
;             ob0 = __builtin_amdgcn_mfma_f32_32x32x16_bf16(v0, fb, ob0, 0, 0, 0);
;             ob1 = __builtin_amdgcn_mfma_f32_32x32x16_bf16(v1, fb, ob1, 0, 0, 0);
.Lat_back_aE:
	v_mfma_f32_32x32x16_bf16 v[32:47], v[196:199], v[112:115], v[32:47]
	v_exp_f32_e32 v64, v64
	v_exp_f32_e32 v65, v65
	v_exp_f32_e32 v66, v66
	v_exp_f32_e32 v67, v67
	v_mfma_f32_32x32x16_bf16 v[0:15], v[200:203], v[112:115], v[0:15]
	v_exp_f32_e32 v68, v68
	v_exp_f32_e32 v69, v69
	v_add_f32_e32 v230, v64, v65
	v_exp_f32_e32 v70, v70
	v_mfma_f32_32x32x16_bf16 v[32:47], v[204:207], v[116:119], v[32:47]
	v_exp_f32_e32 v71, v71
	v_add_f32_e32 v231, v66, v67
	v_exp_f32_e32 v72, v72
	v_exp_f32_e32 v73, v73
	v_mfma_f32_32x32x16_bf16 v[0:15], v[208:211], v[116:119], v[0:15]
	v_add_f32_e32 v230, v230, v68
	v_add3_u32 v225, s34, v187, v128
	ds_read_b128 v[196:199], v225 offset:13312
	ds_read_b128 v[200:203], v225 offset:17920
	ds_read_b128 v[204:207], v225 offset:13344
	ds_read_b128 v[208:211], v225 offset:17952
	v_add_f32_e32 v231, v231, v69
	v_exp_f32_e32 v74, v74
	v_exp_f32_e32 v75, v75
	v_mfma_f32_32x32x16_bf16 v[96:111], v[240:243], v[244:247], 0
	v_add_f32_e32 v230, v230, v70
	v_add_f32_e32 v231, v231, v71
	v_exp_f32_e32 v76, v76
	v_exp_f32_e32 v77, v77
	v_add_f32_e32 v230, v230, v72
	s_waitcnt lgkmcnt(6)
	v_mfma_f32_32x32x16_bf16 v[96:111], v[212:215], v[130:133], v[96:111]
	v_add_f32_e32 v231, v231, v73
	v_exp_f32_e32 v78, v78
	v_exp_f32_e32 v79, v79
	v_add_f32_e32 v230, v230, v74
	v_mfma_f32_32x32x16_bf16 v[112:127], v[212:215], v[138:141], 0
	ds_read_b128 v[212:215], v224 offset:6752
	v_add_f32_e32 v231, v231, v75
	v_add_f32_e32 v230, v230, v76
	v_add_f32_e32 v231, v231, v77
	v_add_f32_e32 v230, v230, v78
	v_add_f32_e32 v231, v231, v79
	s_waitcnt lgkmcnt(6)
	v_mfma_f32_32x32x16_bf16 v[96:111], v[216:219], v[134:137], v[96:111]
	v_add_f32_e32 v230, v230, v231
	v_add_f32_e32 v191, v191, v230
	v_cvt_pk_bf16_f32 v64, v64, v65
	v_cvt_pk_bf16_f32 v65, v66, v67
	v_mfma_f32_32x32x16_bf16 v[112:127], v[216:219], v[142:145], v[112:127]
	ds_read_b128 v[216:219], v224 offset:6784
	v_cvt_pk_bf16_f32 v66, v68, v69
	v_cvt_pk_bf16_f32 v67, v70, v71
	v_cvt_pk_bf16_f32 v68, v72, v73
	v_cvt_pk_bf16_f32 v69, v74, v75
	v_cvt_pk_bf16_f32 v70, v76, v77
	s_waitcnt lgkmcnt(6)
	v_mfma_f32_32x32x16_bf16 v[96:111], v[220:223], v[146:149], v[96:111]
	v_cvt_pk_bf16_f32 v71, v78, v79
	v_max3_f32 v226, v80, v81, v82
	v_max3_f32 v227, v83, v84, v85
	v_max3_f32 v226, v226, v86, v87
	v_mfma_f32_32x32x16_bf16 v[112:127], v[220:223], v[154:157], v[112:127]
	ds_read_b128 v[220:223], v224 offset:6816
	v_max3_f32 v227, v227, v88, v89
	v_max3_f32 v226, v226, v90, v91
	v_max3_f32 v227, v227, v92, v93
	v_max3_f32 v226, v226, v94, v95
	v_max_f32_e32 v226, v226, v227
	s_waitcnt lgkmcnt(2)
	v_mfma_f32_32x32x16_bf16 v[96:111], v[212:215], v[150:153], v[96:111]
	v_cmp_lt_f32_e32 vcc, s33, v226
	s_cbranch_vccnz .Lat_resc_bE
.Lat_back_bE:
	v_exp_f32_e32 v80, v80
	v_exp_f32_e32 v81, v81
	v_exp_f32_e32 v82, v82
	v_mfma_f32_32x32x16_bf16 v[112:127], v[212:215], v[158:161], v[112:127]
	v_exp_f32_e32 v83, v83
	v_exp_f32_e32 v84, v84
	v_exp_f32_e32 v85, v85
	v_add_f32_e32 v230, v80, v81
	v_exp_f32_e32 v86, v86
	s_waitcnt lgkmcnt(1)
	v_mfma_f32_32x32x16_bf16 v[96:111], v[216:219], v[162:165], v[96:111]
	v_exp_f32_e32 v87, v87
	v_add_f32_e32 v231, v82, v83
	v_exp_f32_e32 v88, v88
	v_exp_f32_e32 v89, v89
	v_mfma_f32_32x32x16_bf16 v[112:127], v[216:219], v[170:173], v[112:127]
	v_add_f32_e32 v230, v230, v84
	v_add_f32_e32 v231, v231, v85
	v_exp_f32_e32 v90, v90
	v_exp_f32_e32 v91, v91
	v_add_f32_e32 v230, v230, v86
	s_waitcnt lgkmcnt(0)
	v_mfma_f32_32x32x16_bf16 v[96:111], v[220:223], v[166:169], v[96:111]
	v_add_f32_e32 v231, v231, v87
	v_exp_f32_e32 v92, v92
	v_exp_f32_e32 v93, v93
	v_add_f32_e32 v230, v230, v88
	v_mfma_f32_32x32x16_bf16 v[112:127], v[220:223], v[174:177], v[112:127]
	v_add_f32_e32 v231, v231, v89
	v_exp_f32_e32 v94, v94
	v_exp_f32_e32 v95, v95
	v_add_f32_e32 v230, v230, v90
	v_add_f32_e32 v231, v231, v91
	v_mfma_f32_32x32x16_bf16 v[112:127], v[240:243], v[248:251], v[112:127]
	v_add_f32_e32 v230, v230, v92
	v_add_f32_e32 v231, v231, v93
	v_add_f32_e32 v230, v230, v94
	v_add_f32_e32 v231, v231, v95
	v_add_f32_e32 v230, v230, v231
	v_add_f32_e32 v193, v193, v230
	v_cvt_pk_bf16_f32 v80, v80, v81
	v_cvt_pk_bf16_f32 v81, v82, v83
	v_cvt_pk_bf16_f32 v82, v84, v85
	v_cvt_pk_bf16_f32 v83, v86, v87
	v_cvt_pk_bf16_f32 v84, v88, v89
	v_cvt_pk_bf16_f32 v85, v90, v91
	v_cvt_pk_bf16_f32 v86, v92, v93
	v_cvt_pk_bf16_f32 v87, v94, v95
	s_waitcnt vmcnt(0)
	s_barrier
	s_cmpk_gt_u32 s27, 0x81
	s_cbranch_scc1 .Lat_dma_endL
	s_cmp_lt_u32 s27, 2
	s_cselect_b32 s14, s10, s11
	s_add_i32 s14, s14, s24
	s_and_b64 vcc, exec, s[4:5]
	s_cbranch_vccnz .Lat_dmaL_0
	v_mad_u64_u32 v[234:235], s[16:17], v182, s14, v[180:181]
	s_add_i32 m0, s25, s19
	s_nop 0
	global_load_lds_dwordx4 v[234:235], off

; #define LAS __attribute__((address_space(3)))
; __device__ __forceinline__ void attn_unit2(LAS unsigned char* lds, const bf16_t* __restrict__ Q, const bf16_t* __restrict__ KN, const bf16_t* __restrict__ KPE, ...
;     ...
;         SOFTMAX2(sa0, sa1, ma, la, oa0, oa1, pa);
;         SOFTMAX2(sb0, sb1, mb, lb, ob0, ob1, pb);
;     ...
;         const LAS unsigned char* va = lds + sc + va_off;
; #pragma unroll
;         for (int st = 0; st < 4; ++st) {
;             const bf16x8 v0 = *(const LAS bf16x8*)(va + st * 32);
;             const bf16x8 v1 = *(const LAS bf16x8*)(va + 32 * VROW + st * 32);
;             const bf16x8 fa = __builtin_bit_cast(bf16x8, pa[st]), fb = __builtin_bit_cast(bf16x8, pb[st]);
;             oa0 = __builtin_amdgcn_mfma_f32_32x32x16_bf16(v0, fa, oa0, 0, 0, 0);
;             oa1 = __builtin_amdgcn_mfma_f32_32x32x16_bf16(v1, fa, oa1, 0, 0, 0);
;             ob0 = __builtin_amdgcn_mfma_f32_32x32x16_bf16(v0, fb, ob0, 0, 0, 0);
;             ob1 = __builtin_amdgcn_mfma_f32_32x32x16_bf16(v1, fb, ob1, 0, 0, 0);
;         }
;         __builtin_amdgcn_sched_barrier(0);
;         __syncthreads();
;         { const int tmp = sc; sc = sn; sn = snn; snn = tmp; }
.Lat_dmaL_2:
.Lat_dma_endL:
	v_add3_u32 v224, s26, v183, v128
	ds_read_b128 v[212:215], v224 offset:0
	ds_read_b128 v[216:219], v224 offset:32
	ds_read_b128 v[220:223], v224 offset:64
	v_mfma_f32_32x32x16_bf16 v[16:31], v[196:199], v[64:67], v[16:31]
	v_max3_f32 v226, v96, v97, v98
	v_max3_f32 v227, v99, v100, v101
	v_mfma_f32_32x32x16_bf16 v[48:63], v[200:203], v[64:67], v[48:63]
	v_max3_f32 v226, v226, v102, v103
	v_max3_f32 v227, v227, v104, v105
	v_mfma_f32_32x32x16_bf16 v[16:31], v[204:207], v[68:71], v[16:31]
	v_max3_f32 v226, v226, v106, v107
	v_max3_f32 v227, v227, v108, v109
	v_mfma_f32_32x32x16_bf16 v[48:63], v[208:211], v[68:71], v[48:63]
	v_max3_f32 v226, v226, v110, v111
	v_max_f32_e32 v226, v226, v227
	v_cmp_lt_f32_e32 vcc, s33, v226
	s_cbranch_vccnz .Lat_resc_aO
.Lat_back_aO:
	v_mfma_f32_32x32x16_bf16 v[32:47], v[196:199], v[80:83], v[32:47]
	v_exp_f32_e32 v96, v96
	v_exp_f32_e32 v97, v97
	v_exp_f32_e32 v98, v98
	v_exp_f32_e32 v99, v99
	v_mfma_f32_32x32x16_bf16 v[0:15], v[200:203], v[80:83], v[0:15]
	v_exp_f32_e32 v100, v100
	v_exp_f32_e32 v101, v101
	v_add_f32_e32 v230, v96, v97
	v_exp_f32_e32 v102, v102
	v_mfma_f32_32x32x16_bf16 v[32:47], v[204:207], v[84:87], v[32:47]
	v_exp_f32_e32 v103, v103
	v_add_f32_e32 v231, v98, v99
	v_exp_f32_e32 v104, v104
	v_exp_f32_e32 v105, v105
	v_mfma_f32_32x32x16_bf16 v[0:15], v[208:211], v[84:87], v[0:15]
	v_add_f32_e32 v230, v230, v100
	v_add3_u32 v225, s34, v187, v128
	ds_read_b128 v[196:199], v225 offset:13376
	ds_read_b128 v[200:203], v225 offset:17984
	ds_read_b128 v[204:207], v225 offset:13408
	ds_read_b128 v[208:211], v225 offset:18016
	v_add_f32_e32 v231, v231, v101
	v_exp_f32_e32 v106, v106
	v_exp_f32_e32 v107, v107
	v_mfma_f32_32x32x16_bf16 v[64:79], v[240:243], v[244:247], 0
	v_add_f32_e32 v230, v230, v102
	v_add_f32_e32 v231, v231, v103
	v_exp_f32_e32 v108, v108
	v_exp_f32_e32 v109, v109
	v_add_f32_e32 v230, v230, v104
	s_waitcnt lgkmcnt(6)
	v_mfma_f32_32x32x16_bf16 v[64:79], v[212:215], v[130:133], v[64:79]
	v_add_f32_e32 v231, v231, v105
	v_exp_f32_e32 v110, v110
	v_exp_f32_e32 v111, v111
	v_add_f32_e32 v230, v230, v106
	v_mfma_f32_32x32x16_bf16 v[80:95], v[212:215], v[138:141], 0
	ds_read_b128 v[212:215], v224 offset:96
	v_add_f32_e32 v231, v231, v107
	v_add_f32_e32 v230, v230, v108
	v_add_f32_e32 v231, v231, v109
	v_add_f32_e32 v230, v230, v110
	v_add_f32_e32 v231, v231, v111
	s_waitcnt lgkmcnt(6)
	v_mfma_f32_32x32x16_bf16 v[64:79], v[216:219], v[134:137], v[64:79]
	v_add_f32_e32 v230, v230, v231
	v_add_f32_e32 v191, v191, v230
	v_cvt_pk_bf16_f32 v96, v96, v97
	v_cvt_pk_bf16_f32 v97, v98, v99
	v_mfma_f32_32x32x16_bf16 v[80:95], v[216:219], v[142:145], v[80:95]
	ds_read_b128 v[216:219], v224 offset:128
	v_cvt_pk_bf16_f32 v98, v100, v101
	v_cvt_pk_bf16_f32 v99, v102, v103
	v_cvt_pk_bf16_f32 v100, v104, v105
	v_cvt_pk_bf16_f32 v101, v106, v107
	v_cvt_pk_bf16_f32 v102, v108, v109
	s_waitcnt lgkmcnt(6)
	v_mfma_f32_32x32x16_bf16 v[64:79], v[220:223], v[146:149], v[64:79]
	v_cvt_pk_bf16_f32 v103, v110, v111
	v_max3_f32 v226, v112, v113, v114
	v_max3_f32 v227, v115, v116, v117
	v_max3_f32 v226, v226, v118, v119
	v_mfma_f32_32x32x16_bf16 v[80:95], v[220:223], v[154:157], v[80:95]
	ds_read_b128 v[220:223], v224 offset:160
	v_max3_f32 v227, v227, v120, v121
	v_max3_f32 v226, v226, v122, v123
	v_max3_f32 v227, v227, v124, v125
	v_max3_f32 v226, v226, v126, v127
	v_max_f32_e32 v226, v226, v227
	s_waitcnt lgkmcnt(2)
	v_mfma_f32_32x32x16_bf16 v[64:79], v[212:215], v[150:153], v[64:79]
	v_cmp_lt_f32_e32 vcc, s33, v226
	s_cbranch_vccnz .Lat_resc_bO
.Lat_back_bO:
	v_exp_f32_e32 v112, v112
	v_exp_f32_e32 v113, v113
	v_exp_f32_e32 v114, v114
	v_mfma_f32_32x32x16_bf16 v[80:95], v[212:215], v[158:161], v[80:95]
	v_exp_f32_e32 v115, v115
	v_exp_f32_e32 v116, v116
	v_exp_f32_e32 v117, v117
	v_add_f32_e32 v230, v112, v113
	v_exp_f32_e32 v118, v118
	s_waitcnt lgkmcnt(1)
	v_mfma_f32_32x32x16_bf16 v[64:79], v[216:219], v[162:165], v[64:79]
	v_exp_f32_e32 v119, v119
	v_add_f32_e32 v231, v114, v115
	v_exp_f32_e32 v120, v120
	v_exp_f32_e32 v121, v121
	v_mfma_f32_32x32x16_bf16 v[80:95], v[216:219], v[170:173], v[80:95]
	v_add_f32_e32 v230, v230, v116
	v_add_f32_e32 v231, v231, v117
	v_exp_f32_e32 v122, v122
	v_exp_f32_e32 v123, v123
	v_add_f32_e32 v230, v230, v118
	s_waitcnt lgkmcnt(0)
	v_mfma_f32_32x32x16_bf16 v[64:79], v[220:223], v[166:169], v[64:79]
	v_add_f32_e32 v231, v231, v119
	v_exp_f32_e32 v124, v124
	v_exp_f32_e32 v125, v125
	v_add_f32_e32 v230, v230, v120
	v_mfma_f32_32x32x16_bf16 v[80:95], v[220:223], v[174:177], v[80:95]
	v_add_f32_e32 v231, v231, v121
	v_exp_f32_e32 v126, v126
	v_exp_f32_e32 v127, v127
	v_add_f32_e32 v230, v230, v122
	v_add_f32_e32 v231, v231, v123
	v_mfma_f32_32x32x16_bf16 v[80:95], v[240:243], v[248:251], v[80:95]
	v_add_f32_e32 v230, v230, v124
	v_add_f32_e32 v231, v231, v125
	v_add_f32_e32 v230, v230, v126
	v_add_f32_e32 v231, v231, v127
	v_add_f32_e32 v230, v230, v231
	v_add_f32_e32 v193, v193, v230
	v_cvt_pk_bf16_f32 v112, v112, v113
	v_cvt_pk_bf16_f32 v113, v114, v115
	v_cvt_pk_bf16_f32 v114, v116, v117
	v_cvt_pk_bf16_f32 v115, v118, v119
	v_cvt_pk_bf16_f32 v116, v120, v121
	v_cvt_pk_bf16_f32 v117, v122, v123
	v_cvt_pk_bf16_f32 v118, v124, v125
	v_cvt_pk_bf16_f32 v119, v126, v127
	s_add_i32 s27, s27, 1
	s_add_i32 s24, s24, 64
	s_mov_b32 s14, s34
	s_mov_b32 s34, s26
	s_mov_b32 s26, s25
	s_mov_b32 s25, s14
	s_cmpk_lg_i32 s27, 0x84
	s_cbranch_scc1 .Lat_loop
	s_waitcnt lgkmcnt(3)
	v_mfma_f32_32x32x16_bf16 v[16:31], v[196:199], v[96:99], v[16:31]
	s_waitcnt lgkmcnt(2)
	v_mfma_f32_32x32x16_bf16 v[48:63], v[200:203], v[96:99], v[48:63]
	s_waitcnt lgkmcnt(1)
	v_mfma_f32_32x32x16_bf16 v[16:31], v[204:207], v[100:103], v[16:31]
	s_waitcnt lgkmcnt(0)
	v_mfma_f32_32x32x16_bf16 v[48:63], v[208:211], v[100:103], v[48:63]
	v_mfma_f32_32x32x16_bf16 v[32:47], v[196:199], v[112:115], v[32:47]
	v_mfma_f32_32x32x16_bf16 v[0:15], v[200:203], v[112:115], v[0:15]
	v_mfma_f32_32x32x16_bf16 v[32:47], v[204:207], v[116:119], v[32:47]
	v_mfma_f32_32x32x16_bf16 v[0:15], v[208:211], v[116:119], v[0:15]
	s_branch .Lat_done
.Lat_resc_aE:
	s_nop 15
	v_mov_b32_e32 v227, v226
	s_nop 1
	v_permlane32_swap_b32_e32 v226, v227
	v_max_f32_e32 v226, v226, v227
	v_max_f32_e32 v226, 0, v226
	v_add_f32_e32 v227, v194, v226
	v_cvt_pk_bf16_f32 v227, v227, v227
	v_and_b32_e32 v227, 0xffff0000, v227
	v_sub_f32_e32 v229, v194, v227
	v_mov_b32_e32 v194, v227
	v_exp_f32_e32 v232, v229
	v_add_f32_e32 v64, v64, v229
	v_add_f32_e32 v65, v65, v229
	v_add_f32_e32 v66, v66, v229
	v_add_f32_e32 v67, v67, v229
	v_add_f32_e32 v68, v68, v229
	v_add_f32_e32 v69, v69, v229
	v_add_f32_e32 v70, v70, v229
	v_add_f32_e32 v71, v71, v229
	v_add_f32_e32 v72, v72, v229
	v_add_f32_e32 v73, v73, v229
	v_add_f32_e32 v74, v74, v229
	v_add_f32_e32 v75, v75, v229
	v_add_f32_e32 v76, v76, v229
	v_add_f32_e32 v77, v77, v229
	v_add_f32_e32 v78, v78, v229
	v_add_f32_e32 v79, v79, v229
	v_xor_b32_e32 v227, 0x80000000, v227
	v_lshrrev_b32_e32 v227, 16, v227
	v_and_b32_e32 v244, v228, v227
	v_pk_mul_f32 v[16:17], v[16:17], v[232:233] op_sel_hi:[1,0]
	v_pk_mul_f32 v[18:19], v[18:19], v[232:233] op_sel_hi:[1,0]
	v_pk_mul_f32 v[20:21], v[20:21], v[232:233] op_sel_hi:[1,0]
	v_pk_mul_f32 v[22:23], v[22:23], v[232:233] op_sel_hi:[1,0]
	v_pk_mul_f32 v[24:25], v[24:25], v[232:233] op_sel_hi:[1,0]
	v_pk_mul_f32 v[26:27], v[26:27], v[232:233] op_sel_hi:[1,0]
	v_pk_mul_f32 v[28:29], v[28:29], v[232:233] op_sel_hi:[1,0]
	v_pk_mul_f32 v[30:31], v[30:31], v[232:233] op_sel_hi:[1,0]
	v_pk_mul_f32 v[48:49], v[48:49], v[232:233] op_sel_hi:[1,0]
	v_pk_mul_f32 v[50:51], v[50:51], v[232:233] op_sel_hi:[1,0]
	v_pk_mul_f32 v[52:53], v[52:53], v[232:233] op_sel_hi:[1,0]
	v_pk_mul_f32 v[54:55], v[54:55], v[232:233] op_sel_hi:[1,0]
	v_pk_mul_f32 v[56:57], v[56:57], v[232:233] op_sel_hi:[1,0]
	v_pk_mul_f32 v[58:59], v[58:59], v[232:233] op_sel_hi:[1,0]
	v_pk_mul_f32 v[60:61], v[60:61], v[232:233] op_sel_hi:[1,0]
	v_pk_mul_f32 v[62:63], v[62:63], v[232:233] op_sel_hi:[1,0]
	v_mul_f32_e32 v191, v191, v232
	s_branch .Lat_back_aE
.Lat_resc_bE:
	s_nop 15
	v_mov_b32_e32 v227, v226
	s_nop 1
	v_permlane32_swap_b32_e32 v226, v227
	v_max_f32_e32 v226, v226, v227
	v_max_f32_e32 v226, 0, v226
	v_add_f32_e32 v227, v195, v226
	v_cvt_pk_bf16_f32 v227, v227, v227
	v_and_b32_e32 v227, 0xffff0000, v227
	v_sub_f32_e32 v229, v195, v227
	v_mov_b32_e32 v195, v227
	v_exp_f32_e32 v232, v229
	v_add_f32_e32 v80, v80, v229
	v_add_f32_e32 v81, v81, v229
	v_add_f32_e32 v82, v82, v229
	v_add_f32_e32 v83, v83, v229
	v_add_f32_e32 v84, v84, v229
	v_add_f32_e32 v85, v85, v229
	v_add_f32_e32 v86, v86, v229
	v_add_f32_e32 v87, v87, v229
	v_add_f32_e32 v88, v88, v229
	v_add_f32_e32 v89, v89, v229
	v_add_f32_e32 v90, v90, v229
	v_add_f32_e32 v91, v91, v229
	v_add_f32_e32 v92, v92, v229
	v_add_f32_e32 v93, v93, v229
	v_add_f32_e32 v94, v94, v229
	v_add_f32_e32 v95, v95, v229
	v_xor_b32_e32 v227, 0x80000000, v227
	v_lshrrev_b32_e32 v227, 16, v227
	v_and_b32_e32 v248, v228, v227
	v_pk_mul_f32 v[32:33], v[32:33], v[232:233] op_sel_hi:[1,0]
	v_pk_mul_f32 v[34:35], v[34:35], v[232:233] op_sel_hi:[1,0]
	v_pk_mul_f32 v[36:37], v[36:37], v[232:233] op_sel_hi:[1,0]
	v_pk_mul_f32 v[38:39], v[38:39], v[232:233] op_sel_hi:[1,0]
	v_pk_mul_f32 v[40:41], v[40:41], v[232:233] op_sel_hi:[1,0]
	v_pk_mul_f32 v[42:43], v[42:43], v[232:233] op_sel_hi:[1,0]
	v_pk_mul_f32 v[44:45], v[44:45], v[232:233] op_sel_hi:[1,0]
	v_pk_mul_f32 v[46:47], v[46:47], v[232:233] op_sel_hi:[1,0]
	v_pk_mul_f32 v[0:1], v[0:1], v[232:233] op_sel_hi:[1,0]
	v_pk_mul_f32 v[2:3], v[2:3], v[232:233] op_sel_hi:[1,0]
	v_pk_mul_f32 v[4:5], v[4:5], v[232:233] op_sel_hi:[1,0]
	v_pk_mul_f32 v[6:7], v[6:7], v[232:233] op_sel_hi:[1,0]
	v_pk_mul_f32 v[8:9], v[8:9], v[232:233] op_sel_hi:[1,0]
	v_pk_mul_f32 v[10:11], v[10:11], v[232:233] op_sel_hi:[1,0]
	v_pk_mul_f32 v[12:13], v[12:13], v[232:233] op_sel_hi:[1,0]
	v_pk_mul_f32 v[14:15], v[14:15], v[232:233] op_sel_hi:[1,0]
	v_mul_f32_e32 v193, v193, v232
	s_branch .Lat_back_bE
.Lat_resc_aO:
	s_nop 15
	v_mov_b32_e32 v227, v226
	s_nop 1
	v_permlane32_swap_b32_e32 v226, v227
	v_max_f32_e32 v226, v226, v227
	v_max_f32_e32 v226, 0, v226
	v_add_f32_e32 v227, v194, v226
	v_cvt_pk_bf16_f32 v227, v227, v227
	v_and_b32_e32 v227, 0xffff0000, v227
	v_sub_f32_e32 v229, v194, v227
	v_mov_b32_e32 v194, v227
	v_exp_f32_e32 v232, v229
	v_add_f32_e32 v96, v96, v229
	v_add_f32_e32 v97, v97, v229
	v_add_f32_e32 v98, v98, v229
	v_add_f32_e32 v99, v99, v229
	v_add_f32_e32 v100, v100, v229
	v_add_f32_e32 v101, v101, v229
	v_add_f32_e32 v102, v102, v229
	v_add_f32_e32 v103, v103, v229
	v_add_f32_e32 v104, v104, v229
	v_add_f32_e32 v105, v105, v229
	v_add_f32_e32 v106, v106, v229
	v_add_f32_e32 v107, v107, v229
	v_add_f32_e32 v108, v108, v229
	v_add_f32_e32 v109, v109, v229
	v_add_f32_e32 v110, v110, v229
	v_add_f32_e32 v111, v111, v229
	v_xor_b32_e32 v227, 0x80000000, v227
	v_lshrrev_b32_e32 v227, 16, v227
	v_and_b32_e32 v244, v228, v227
	v_pk_mul_f32 v[16:17], v[16:17], v[232:233] op_sel_hi:[1,0]
	v_pk_mul_f32 v[18:19], v[18:19], v[232:233] op_sel_hi:[1,0]
	v_pk_mul_f32 v[20:21], v[20:21], v[232:233] op_sel_hi:[1,0]
	v_pk_mul_f32 v[22:23], v[22:23], v[232:233] op_sel_hi:[1,0]
	v_pk_mul_f32 v[24:25], v[24:25], v[232:233] op_sel_hi:[1,0]
	v_pk_mul_f32 v[26:27], v[26:27], v[232:233] op_sel_hi:[1,0]
	v_pk_mul_f32 v[28:29], v[28:29], v[232:233] op_sel_hi:[1,0]
	v_pk_mul_f32 v[30:31], v[30:31], v[232:233] op_sel_hi:[1,0]
	v_pk_mul_f32 v[48:49], v[48:49], v[232:233] op_sel_hi:[1,0]
	v_pk_mul_f32 v[50:51], v[50:51], v[232:233] op_sel_hi:[1,0]
	v_pk_mul_f32 v[52:53], v[52:53], v[232:233] op_sel_hi:[1,0]
	v_pk_mul_f32 v[54:55], v[54:55], v[232:233] op_sel_hi:[1,0]
	v_pk_mul_f32 v[56:57], v[56:57], v[232:233] op_sel_hi:[1,0]
	v_pk_mul_f32 v[58:59], v[58:59], v[232:233] op_sel_hi:[1,0]
	v_pk_mul_f32 v[60:61], v[60:61], v[232:233] op_sel_hi:[1,0]
	v_pk_mul_f32 v[62:63], v[62:63], v[232:233] op_sel_hi:[1,0]
	v_mul_f32_e32 v191, v191, v232
	s_branch .Lat_back_aO
.Lat_resc_bO:
	s_nop 15
	v_mov_b32_e32 v227, v226
	s_nop 1
	v_permlane32_swap_b32_e32 v226, v227
	v_max_f32_e32 v226, v226, v227
	v_max_f32_e32 v226, 0, v226
	v_add_f32_e32 v227, v195, v226
	v_cvt_pk_bf16_f32 v227, v227, v227
	v_and_b32_e32 v227, 0xffff0000, v227
	v_sub_f32_e32 v229, v195, v227
	v_mov_b32_e32 v195, v227
	v_exp_f32_e32 v232, v229
	v_add_f32_e32 v112, v112, v229
	v_add_f32_e32 v113, v113, v229
	v_add_f32_e32 v114, v114, v229
	v_add_f32_e32 v115, v115, v229
	v_add_f32_e32 v116, v116, v229
	v_add_f32_e32 v117, v117, v229
	v_add_f32_e32 v118, v118, v229
	v_add_f32_e32 v119, v119, v229
	v_add_f32_e32 v120, v120, v229
	v_add_f32_e32 v121, v121, v229
	v_add_f32_e32 v122, v122, v229
	v_add_f32_e32 v123, v123, v229
	v_add_f32_e32 v124, v124, v229
	v_add_f32_e32 v125, v125, v229
	v_add_f32_e32 v126, v126, v229
	v_add_f32_e32 v127, v127, v229
	v_xor_b32_e32 v227, 0x80000000, v227
	v_lshrrev_b32_e32 v227, 16, v227
	v_and_b32_e32 v248, v228, v227
	v_pk_mul_f32 v[32:33], v[32:33], v[232:233] op_sel_hi:[1,0]
	v_pk_mul_f32 v[34:35], v[34:35], v[232:233] op_sel_hi:[1,0]
	v_pk_mul_f32 v[36:37], v[36:37], v[232:233] op_sel_hi:[1,0]
	v_pk_mul_f32 v[38:39], v[38:39], v[232:233] op_sel_hi:[1,0]
	v_pk_mul_f32 v[40:41], v[40:41], v[232:233] op_sel_hi:[1,0]
	v_pk_mul_f32 v[42:43], v[42:43], v[232:233] op_sel_hi:[1,0]
	v_pk_mul_f32 v[44:45], v[44:45], v[232:233] op_sel_hi:[1,0]
	v_pk_mul_f32 v[46:47], v[46:47], v[232:233] op_sel_hi:[1,0]
	v_pk_mul_f32 v[0:1], v[0:1], v[232:233] op_sel_hi:[1,0]
	v_pk_mul_f32 v[2:3], v[2:3], v[232:233] op_sel_hi:[1,0]
	v_pk_mul_f32 v[4:5], v[4:5], v[232:233] op_sel_hi:[1,0]
	v_pk_mul_f32 v[6:7], v[6:7], v[232:233] op_sel_hi:[1,0]
	v_pk_mul_f32 v[8:9], v[8:9], v[232:233] op_sel_hi:[1,0]
	v_pk_mul_f32 v[10:11], v[10:11], v[232:233] op_sel_hi:[1,0]
	v_pk_mul_f32 v[12:13], v[12:13], v[232:233] op_sel_hi:[1,0]
	v_pk_mul_f32 v[14:15], v[14:15], v[232:233] op_sel_hi:[1,0]
	v_mul_f32_e32 v193, v193, v232
	s_branch .Lat_back_bO
